# GEMM K-loops: removed the back-to-back s_setprio 0 / s_setprio 1 pair in the middle of each 32-MFMA block
# speedup vs baseline: 1.0116x; 1.0035x over previous
.LBB0_129:
	s_add_u32 s44, s80, 0xfffc0080
	s_addc_u32 s45, s81, -1
	s_add_i32 s88, 0, 0x10000
	s_cmp_eq_u32 s87, 12
	s_cselect_b32 s85, s30, s45
	s_cselect_b32 s84, s47, s44
	v_add_u32_e32 v0, s88, v233
	s_cselect_b32 s83, s49, s86
	s_cselect_b32 s82, s71, s73
	s_add_i32 s89, 0, 0x14000
	ds_read_b128 v[148:151], v0
	ds_read_b128 v[152:155], v0 offset:1024
	ds_read_b128 v[156:159], v0 offset:2048
	ds_read_b128 v[160:163], v0 offset:3072
	v_add_u32_e32 v0, s89, v233
	s_waitcnt lgkmcnt(0)
	ds_read_b128 v[132:135], v0
	ds_read_b128 v[136:139], v0 offset:1024
	ds_read_b128 v[140:143], v0 offset:2048
	ds_read_b128 v[144:147], v0 offset:3072
	v_lshl_add_u64 v[2:3], s[80:81], 0, v[214:215]
	s_add_i32 m0, s97, 0xc000
	ds_read_b128 v[164:167], v237
	ds_read_b128 v[168:171], v237 offset:1024
	ds_read_b128 v[172:175], v237 offset:2048
	ds_read_b128 v[176:179], v237 offset:3072
	ds_read_b128 v[180:183], v237 offset:4096
	ds_read_b128 v[184:187], v237 offset:5120
	ds_read_b128 v[188:191], v237 offset:6144
	ds_read_b128 v[192:195], v237 offset:7168
	global_load_lds_dwordx4 v[2:3], off
	v_lshl_add_u64 v[2:3], s[80:81], 0, v[216:217]
	s_add_i32 m0, s97, 0xe000
	s_nop 0
	global_load_lds_dwordx4 v[2:3], off
	s_waitcnt vmcnt(8)
	s_waitcnt lgkmcnt(0)
	s_barrier
	s_setprio 1
	s_waitcnt lgkmcnt(0)
	v_mfma_f32_16x16x32_bf16 v[128:131], v[148:151], v[164:167], v[128:131]
	v_mfma_f32_16x16x32_bf16 v[120:123], v[156:159], v[164:167], v[120:123]
	v_mfma_f32_16x16x32_bf16 v[124:127], v[148:151], v[172:175], v[124:127]
	v_mfma_f32_16x16x32_bf16 v[116:119], v[156:159], v[172:175], v[116:119]
	v_mfma_f32_16x16x32_bf16 v[96:99], v[148:151], v[180:183], v[96:99]
	v_mfma_f32_16x16x32_bf16 v[88:91], v[156:159], v[180:183], v[88:91]
	v_mfma_f32_16x16x32_bf16 v[92:95], v[148:151], v[188:191], v[92:95]
	v_mfma_f32_16x16x32_bf16 v[84:87], v[156:159], v[188:191], v[84:87]
	v_mfma_f32_16x16x32_bf16 v[128:131], v[152:155], v[168:171], v[128:131]
	v_mfma_f32_16x16x32_bf16 v[120:123], v[160:163], v[168:171], v[120:123]
	v_mfma_f32_16x16x32_bf16 v[124:127], v[152:155], v[176:179], v[124:127]
	v_mfma_f32_16x16x32_bf16 v[116:119], v[160:163], v[176:179], v[116:119]
	v_mfma_f32_16x16x32_bf16 v[96:99], v[152:155], v[184:187], v[96:99]
	v_mfma_f32_16x16x32_bf16 v[88:91], v[160:163], v[184:187], v[88:91]
	v_mfma_f32_16x16x32_bf16 v[92:95], v[152:155], v[192:195], v[92:95]
	v_mfma_f32_16x16x32_bf16 v[84:87], v[160:163], v[192:195], v[84:87]
	v_mfma_f32_16x16x32_bf16 v[112:115], v[132:135], v[164:167], v[112:115]
	v_mfma_f32_16x16x32_bf16 v[104:107], v[140:143], v[164:167], v[104:107]
	v_mfma_f32_16x16x32_bf16 v[108:111], v[132:135], v[172:175], v[108:111]
	v_mfma_f32_16x16x32_bf16 v[100:103], v[140:143], v[172:175], v[100:103]
	v_mfma_f32_16x16x32_bf16 v[80:83], v[132:135], v[180:183], v[80:83]
	v_mfma_f32_16x16x32_bf16 v[72:75], v[140:143], v[180:183], v[72:75]
	v_mfma_f32_16x16x32_bf16 v[76:79], v[132:135], v[188:191], v[76:79]
	v_mfma_f32_16x16x32_bf16 v[68:71], v[140:143], v[188:191], v[68:71]
	v_mfma_f32_16x16x32_bf16 v[112:115], v[136:139], v[168:171], v[112:115]
	v_mfma_f32_16x16x32_bf16 v[104:107], v[144:147], v[168:171], v[104:107]
	v_mfma_f32_16x16x32_bf16 v[108:111], v[136:139], v[176:179], v[108:111]
	v_mfma_f32_16x16x32_bf16 v[100:103], v[144:147], v[176:179], v[100:103]
	v_mfma_f32_16x16x32_bf16 v[80:83], v[136:139], v[184:187], v[80:83]
	v_mfma_f32_16x16x32_bf16 v[72:75], v[144:147], v[184:187], v[72:75]
	v_mfma_f32_16x16x32_bf16 v[76:79], v[136:139], v[192:195], v[76:79]
	v_mfma_f32_16x16x32_bf16 v[68:71], v[144:147], v[192:195], v[68:71]
	s_setprio 0
	s_barrier
	s_add_i32 s44, s88, s96
	v_lshl_add_u64 v[2:3], s[82:83], 0, v[208:209]
	s_mov_b32 m0, s44
	ds_read_b128 v[188:191], v237 offset:16384
	ds_read_b128 v[192:195], v237 offset:17408
	ds_read_b128 v[180:183], v237 offset:18432
	ds_read_b128 v[184:187], v237 offset:19456
	ds_read_b128 v[172:175], v237 offset:20480
	ds_read_b128 v[176:179], v237 offset:21504
	ds_read_b128 v[164:167], v237 offset:22528
	ds_read_b128 v[168:171], v237 offset:23552
	global_load_lds_dwordx4 v[2:3], off
	s_add_i32 m0, s44, 0x2000
	s_add_u32 s44, s82, 0x40000
	v_lshl_add_u64 v[218:219], s[82:83], 0, v[212:213]
	s_addc_u32 s45, s83, 0
	s_add_i32 s88, s89, s96
	global_load_lds_dwordx4 v[218:219], off
	v_lshl_add_u64 v[220:221], s[44:45], 0, v[208:209]
	s_mov_b32 m0, s88
	v_lshl_add_u64 v[222:223], s[84:85], 0, v[210:211]
	global_load_lds_dwordx4 v[220:221], off
	v_lshl_add_u64 v[220:221], s[44:45], 0, v[212:213]
	s_add_i32 m0, s88, 0x2000
	v_cndmask_b32_e64 v0, 0, 1, s[50:51]
	global_load_lds_dwordx4 v[220:221], off
	v_lshl_add_u64 v[220:221], s[84:85], 0, v[206:207]
	s_mov_b32 m0, s97
	v_cmp_ne_u32_e64 s[44:45], 1, v0
	global_load_lds_dwordx4 v[220:221], off
	s_mov_b32 m0, s25
	s_andn2_b64 vcc, exec, s[50:51]
	global_load_lds_dwordx4 v[222:223], off
	s_waitcnt vmcnt(8)
	s_waitcnt lgkmcnt(0)
	s_barrier
	s_cbranch_vccnz .LBB0_131
	s_setprio 1
	s_waitcnt lgkmcnt(0)
	v_mfma_f32_16x16x32_bf16 v[64:67], v[148:151], v[188:191], v[64:67]
	v_mfma_f32_16x16x32_bf16 v[56:59], v[156:159], v[188:191], v[56:59]
	v_mfma_f32_16x16x32_bf16 v[60:63], v[148:151], v[180:183], v[60:63]
	v_mfma_f32_16x16x32_bf16 v[52:55], v[156:159], v[180:183], v[52:55]
	v_mfma_f32_16x16x32_bf16 v[32:35], v[148:151], v[172:175], v[32:35]
	v_mfma_f32_16x16x32_bf16 v[24:27], v[156:159], v[172:175], v[24:27]
	v_mfma_f32_16x16x32_bf16 v[28:31], v[148:151], v[164:167], v[28:31]
	v_mfma_f32_16x16x32_bf16 v[20:23], v[156:159], v[164:167], v[20:23]
	v_mfma_f32_16x16x32_bf16 v[64:67], v[152:155], v[192:195], v[64:67]
	v_mfma_f32_16x16x32_bf16 v[56:59], v[160:163], v[192:195], v[56:59]
	v_mfma_f32_16x16x32_bf16 v[60:63], v[152:155], v[184:187], v[60:63]
	v_mfma_f32_16x16x32_bf16 v[52:55], v[160:163], v[184:187], v[52:55]
	v_mfma_f32_16x16x32_bf16 v[32:35], v[152:155], v[176:179], v[32:35]
	v_mfma_f32_16x16x32_bf16 v[24:27], v[160:163], v[176:179], v[24:27]
	v_mfma_f32_16x16x32_bf16 v[28:31], v[152:155], v[168:171], v[28:31]
	v_mfma_f32_16x16x32_bf16 v[20:23], v[160:163], v[168:171], v[20:23]
	v_mfma_f32_16x16x32_bf16 v[48:51], v[132:135], v[188:191], v[48:51]
	v_mfma_f32_16x16x32_bf16 v[40:43], v[140:143], v[188:191], v[40:43]
	v_mfma_f32_16x16x32_bf16 v[44:47], v[132:135], v[180:183], v[44:47]
	v_mfma_f32_16x16x32_bf16 v[36:39], v[140:143], v[180:183], v[36:39]
	v_mfma_f32_16x16x32_bf16 v[16:19], v[132:135], v[172:175], v[16:19]
	v_mfma_f32_16x16x32_bf16 v[8:11], v[140:143], v[172:175], v[8:11]
	v_mfma_f32_16x16x32_bf16 v[12:15], v[132:135], v[164:167], v[12:15]
	v_mfma_f32_16x16x32_bf16 v[4:7], v[140:143], v[164:167], v[4:7]
	v_mfma_f32_16x16x32_bf16 v[48:51], v[136:139], v[192:195], v[48:51]
	v_mfma_f32_16x16x32_bf16 v[40:43], v[144:147], v[192:195], v[40:43]
	v_mfma_f32_16x16x32_bf16 v[44:47], v[136:139], v[184:187], v[44:47]
	v_mfma_f32_16x16x32_bf16 v[36:39], v[144:147], v[184:187], v[36:39]
	v_mfma_f32_16x16x32_bf16 v[16:19], v[136:139], v[176:179], v[16:19]
	v_mfma_f32_16x16x32_bf16 v[8:11], v[144:147], v[176:179], v[8:11]
	v_mfma_f32_16x16x32_bf16 v[12:15], v[136:139], v[168:171], v[12:15]
	v_mfma_f32_16x16x32_bf16 v[4:7], v[144:147], v[168:171], v[4:7]
	s_setprio 0
.LBB0_131:
	s_barrier
	s_add_i32 s88, 0, 0x18000
	v_add_u32_e32 v0, s88, v233
	s_add_i32 s89, 0, 0x1c000
	ds_read_b128 v[148:151], v0
	ds_read_b128 v[152:155], v0 offset:1024
	ds_read_b128 v[156:159], v0 offset:2048
	ds_read_b128 v[160:163], v0 offset:3072
	v_add_u32_e32 v0, s89, v233
	ds_read_b128 v[132:135], v0
	ds_read_b128 v[136:139], v0 offset:1024
	ds_read_b128 v[140:143], v0 offset:2048
	ds_read_b128 v[144:147], v0 offset:3072
	s_add_u32 s84, s84, 0x40000
	s_addc_u32 s85, s85, 0
	s_mov_b32 m0, s55
	v_lshl_add_u64 v[238:239], s[84:85], 0, v[206:207]
	s_waitcnt lgkmcnt(0)
	ds_read_b128 v[164:167], v237 offset:32768
	ds_read_b128 v[168:171], v237 offset:33792
	ds_read_b128 v[172:175], v237 offset:34816
	ds_read_b128 v[176:179], v237 offset:35840
	ds_read_b128 v[180:183], v237 offset:36864
	ds_read_b128 v[184:187], v237 offset:37888
	ds_read_b128 v[188:191], v237 offset:38912
	ds_read_b128 v[192:195], v237 offset:39936
	global_load_lds_dwordx4 v[238:239], off
	v_lshl_add_u64 v[238:239], s[84:85], 0, v[210:211]
	s_mov_b32 m0, s92
	s_nop 0
	global_load_lds_dwordx4 v[238:239], off
	s_waitcnt vmcnt(8)
	s_waitcnt lgkmcnt(0)
	s_barrier
	s_setprio 1
	s_waitcnt lgkmcnt(0)
	v_mfma_f32_16x16x32_bf16 v[128:131], v[148:151], v[164:167], v[128:131]
	v_mfma_f32_16x16x32_bf16 v[120:123], v[156:159], v[164:167], v[120:123]
	v_mfma_f32_16x16x32_bf16 v[124:127], v[148:151], v[172:175], v[124:127]
	v_mfma_f32_16x16x32_bf16 v[116:119], v[156:159], v[172:175], v[116:119]
	v_mfma_f32_16x16x32_bf16 v[96:99], v[148:151], v[180:183], v[96:99]
	v_mfma_f32_16x16x32_bf16 v[88:91], v[156:159], v[180:183], v[88:91]
	v_mfma_f32_16x16x32_bf16 v[92:95], v[148:151], v[188:191], v[92:95]
	v_mfma_f32_16x16x32_bf16 v[84:87], v[156:159], v[188:191], v[84:87]
	v_mfma_f32_16x16x32_bf16 v[128:131], v[152:155], v[168:171], v[128:131]
	v_mfma_f32_16x16x32_bf16 v[120:123], v[160:163], v[168:171], v[120:123]
	v_mfma_f32_16x16x32_bf16 v[124:127], v[152:155], v[176:179], v[124:127]
	v_mfma_f32_16x16x32_bf16 v[116:119], v[160:163], v[176:179], v[116:119]
	v_mfma_f32_16x16x32_bf16 v[96:99], v[152:155], v[184:187], v[96:99]
	v_mfma_f32_16x16x32_bf16 v[88:91], v[160:163], v[184:187], v[88:91]
	v_mfma_f32_16x16x32_bf16 v[92:95], v[152:155], v[192:195], v[92:95]
	v_mfma_f32_16x16x32_bf16 v[84:87], v[160:163], v[192:195], v[84:87]
	v_mfma_f32_16x16x32_bf16 v[112:115], v[132:135], v[164:167], v[112:115]
	v_mfma_f32_16x16x32_bf16 v[104:107], v[140:143], v[164:167], v[104:107]
	v_mfma_f32_16x16x32_bf16 v[108:111], v[132:135], v[172:175], v[108:111]
	v_mfma_f32_16x16x32_bf16 v[100:103], v[140:143], v[172:175], v[100:103]
	v_mfma_f32_16x16x32_bf16 v[80:83], v[132:135], v[180:183], v[80:83]
	v_mfma_f32_16x16x32_bf16 v[72:75], v[140:143], v[180:183], v[72:75]
	v_mfma_f32_16x16x32_bf16 v[76:79], v[132:135], v[188:191], v[76:79]
	v_mfma_f32_16x16x32_bf16 v[68:71], v[140:143], v[188:191], v[68:71]
	v_mfma_f32_16x16x32_bf16 v[112:115], v[136:139], v[168:171], v[112:115]
	v_mfma_f32_16x16x32_bf16 v[104:107], v[144:147], v[168:171], v[104:107]
	v_mfma_f32_16x16x32_bf16 v[108:111], v[136:139], v[176:179], v[108:111]
	v_mfma_f32_16x16x32_bf16 v[100:103], v[144:147], v[176:179], v[100:103]
	v_mfma_f32_16x16x32_bf16 v[80:83], v[136:139], v[184:187], v[80:83]
	v_mfma_f32_16x16x32_bf16 v[72:75], v[144:147], v[184:187], v[72:75]
	v_mfma_f32_16x16x32_bf16 v[76:79], v[136:139], v[192:195], v[76:79]
	v_mfma_f32_16x16x32_bf16 v[68:71], v[144:147], v[192:195], v[68:71]
	s_setprio 0
	s_barrier
	s_add_i32 s84, s88, s96
	v_lshl_add_u64 v[2:3], v[2:3], 0, s[58:59]
	s_mov_b32 m0, s84
	ds_read_b128 v[188:191], v237 offset:49152
	ds_read_b128 v[192:195], v237 offset:50176
	ds_read_b128 v[180:183], v237 offset:51200
	ds_read_b128 v[184:187], v237 offset:52224
	ds_read_b128 v[172:175], v237 offset:53248
	ds_read_b128 v[176:179], v237 offset:54272
	ds_read_b128 v[164:167], v237 offset:55296
	ds_read_b128 v[168:171], v237 offset:56320
	global_load_lds_dwordx4 v[2:3], off
	s_add_i32 m0, s84, 0x2000
	s_add_u32 s82, s82, 0x40080
	v_lshl_add_u64 v[2:3], v[218:219], 0, s[58:59]
	s_addc_u32 s83, s83, 0
	s_add_i32 s84, s89, s96
	global_load_lds_dwordx4 v[2:3], off
	v_lshl_add_u64 v[2:3], s[82:83], 0, v[208:209]
	s_mov_b32 m0, s84
	s_and_b64 vcc, exec, s[44:45]
	global_load_lds_dwordx4 v[2:3], off
	v_lshl_add_u64 v[2:3], s[82:83], 0, v[212:213]
	s_add_i32 m0, s84, 0x2000
	s_nop 0
	global_load_lds_dwordx4 v[2:3], off
	v_lshl_add_u64 v[2:3], v[220:221], 0, s[58:59]
	s_mov_b32 m0, s61
	s_nop 0
	global_load_lds_dwordx4 v[2:3], off
	v_lshl_add_u64 v[2:3], v[222:223], 0, s[58:59]
	s_mov_b32 m0, s13
	s_nop 0
	global_load_lds_dwordx4 v[2:3], off
	s_waitcnt vmcnt(8)
	s_waitcnt lgkmcnt(0)
	s_barrier
	s_cbranch_vccnz .LBB0_128
	s_setprio 1
	s_waitcnt lgkmcnt(0)
	v_mfma_f32_16x16x32_bf16 v[64:67], v[148:151], v[188:191], v[64:67]
	v_mfma_f32_16x16x32_bf16 v[56:59], v[156:159], v[188:191], v[56:59]
	v_mfma_f32_16x16x32_bf16 v[60:63], v[148:151], v[180:183], v[60:63]
	v_mfma_f32_16x16x32_bf16 v[52:55], v[156:159], v[180:183], v[52:55]
	v_mfma_f32_16x16x32_bf16 v[32:35], v[148:151], v[172:175], v[32:35]
	v_mfma_f32_16x16x32_bf16 v[24:27], v[156:159], v[172:175], v[24:27]
	v_mfma_f32_16x16x32_bf16 v[28:31], v[148:151], v[164:167], v[28:31]
	v_mfma_f32_16x16x32_bf16 v[20:23], v[156:159], v[164:167], v[20:23]
	v_mfma_f32_16x16x32_bf16 v[64:67], v[152:155], v[192:195], v[64:67]
	v_mfma_f32_16x16x32_bf16 v[56:59], v[160:163], v[192:195], v[56:59]
	v_mfma_f32_16x16x32_bf16 v[60:63], v[152:155], v[184:187], v[60:63]
	v_mfma_f32_16x16x32_bf16 v[52:55], v[160:163], v[184:187], v[52:55]
	v_mfma_f32_16x16x32_bf16 v[32:35], v[152:155], v[176:179], v[32:35]
	v_mfma_f32_16x16x32_bf16 v[24:27], v[160:163], v[176:179], v[24:27]
	v_mfma_f32_16x16x32_bf16 v[28:31], v[152:155], v[168:171], v[28:31]
	v_mfma_f32_16x16x32_bf16 v[20:23], v[160:163], v[168:171], v[20:23]
	v_mfma_f32_16x16x32_bf16 v[48:51], v[132:135], v[188:191], v[48:51]
	v_mfma_f32_16x16x32_bf16 v[40:43], v[140:143], v[188:191], v[40:43]
	v_mfma_f32_16x16x32_bf16 v[44:47], v[132:135], v[180:183], v[44:47]
	v_mfma_f32_16x16x32_bf16 v[36:39], v[140:143], v[180:183], v[36:39]
	v_mfma_f32_16x16x32_bf16 v[16:19], v[132:135], v[172:175], v[16:19]
	v_mfma_f32_16x16x32_bf16 v[8:11], v[140:143], v[172:175], v[8:11]
	v_mfma_f32_16x16x32_bf16 v[12:15], v[132:135], v[164:167], v[12:15]
	v_mfma_f32_16x16x32_bf16 v[2:5], v[140:143], v[164:167], v[4:7]
	v_mfma_f32_16x16x32_bf16 v[48:51], v[136:139], v[192:195], v[48:51]
	v_mfma_f32_16x16x32_bf16 v[40:43], v[144:147], v[192:195], v[40:43]
	v_mfma_f32_16x16x32_bf16 v[44:47], v[136:139], v[184:187], v[44:47]
	v_mfma_f32_16x16x32_bf16 v[36:39], v[144:147], v[184:187], v[36:39]
	v_mfma_f32_16x16x32_bf16 v[16:19], v[136:139], v[176:179], v[16:19]
	v_mfma_f32_16x16x32_bf16 v[8:11], v[144:147], v[176:179], v[8:11]
	v_mfma_f32_16x16x32_bf16 v[12:15], v[136:139], v[168:171], v[12:15]
	v_mfma_f32_16x16x32_bf16 v[4:7], v[144:147], v[168:171], v[2:5]
	s_setprio 0
	s_branch .LBB0_128

.LBB0_537:
	s_add_u32 s62, s60, 0xfffc0080
	s_addc_u32 s63, s61, -1
	s_add_i32 s76, 0, 0x10000
	s_cmp_eq_u32 s75, 12
	s_cselect_b32 s65, s45, s63
	s_cselect_b32 s64, s71, s62
	s_cselect_b32 s63, s43, s74
	s_cselect_b32 s62, s72, s73
	s_add_i32 s78, 0, 0x14000
	v_add_u32_e32 v102, s76, v160
	v_add_u32_e32 v158, s78, v160
	ds_read_b128 v[90:93], v102
	ds_read_b128 v[94:97], v102 offset:1024
	ds_read_b128 v[98:101], v102 offset:2048
	ds_read_b128 v[102:105], v102 offset:3072
	ds_read_b128 v[164:167], v158
	ds_read_b128 v[168:171], v158 offset:1024
	ds_read_b128 v[172:175], v158 offset:2048
	ds_read_b128 v[176:179], v158 offset:3072
	v_lshl_add_u64 v[158:159], s[60:61], 0, v[154:155]
	s_add_i32 m0, s55, 0xc000
	ds_read_b128 v[180:183], v162
	ds_read_b128 v[184:187], v162 offset:1024
	ds_read_b128 v[188:191], v162 offset:2048
	ds_read_b128 v[192:195], v162 offset:3072
	ds_read_b128 v[206:209], v162 offset:4096
	ds_read_b128 v[210:213], v162 offset:5120
	ds_read_b128 v[214:217], v162 offset:6144
	ds_read_b128 v[218:221], v162 offset:7168
	global_load_lds_dwordx4 v[158:159], off
	v_lshl_add_u64 v[158:159], s[60:61], 0, v[156:157]
	s_add_i32 m0, s55, 0xe000
	s_nop 0
	global_load_lds_dwordx4 v[158:159], off
	s_waitcnt vmcnt(8)
	s_waitcnt lgkmcnt(0)
	s_barrier
	s_setprio 1
	s_waitcnt lgkmcnt(0)
	v_mfma_f32_16x16x32_bf16 v[142:145], v[90:93], v[180:183], v[142:145]
	v_mfma_f32_16x16x32_bf16 v[138:141], v[98:101], v[180:183], v[138:141]
	v_mfma_f32_16x16x32_bf16 v[126:129], v[90:93], v[188:191], v[126:129]
	v_mfma_f32_16x16x32_bf16 v[122:125], v[98:101], v[188:191], v[122:125]
	v_mfma_f32_16x16x32_bf16 v[110:113], v[90:93], v[206:209], v[110:113]
	v_mfma_f32_16x16x32_bf16 v[106:109], v[98:101], v[206:209], v[106:109]
	v_mfma_f32_16x16x32_bf16 v[78:81], v[90:93], v[214:217], v[78:81]
	v_mfma_f32_16x16x32_bf16 v[74:77], v[98:101], v[214:217], v[74:77]
	v_mfma_f32_16x16x32_bf16 v[142:145], v[94:97], v[184:187], v[142:145]
	v_mfma_f32_16x16x32_bf16 v[138:141], v[102:105], v[184:187], v[138:141]
	v_mfma_f32_16x16x32_bf16 v[126:129], v[94:97], v[192:195], v[126:129]
	v_mfma_f32_16x16x32_bf16 v[122:125], v[102:105], v[192:195], v[122:125]
	v_mfma_f32_16x16x32_bf16 v[110:113], v[94:97], v[210:213], v[110:113]
	v_mfma_f32_16x16x32_bf16 v[106:109], v[102:105], v[210:213], v[106:109]
	v_mfma_f32_16x16x32_bf16 v[78:81], v[94:97], v[218:221], v[78:81]
	v_mfma_f32_16x16x32_bf16 v[74:77], v[102:105], v[218:221], v[74:77]
	v_mfma_f32_16x16x32_bf16 v[134:137], v[164:167], v[180:183], v[134:137]
	v_mfma_f32_16x16x32_bf16 v[130:133], v[172:175], v[180:183], v[130:133]
	v_mfma_f32_16x16x32_bf16 v[118:121], v[164:167], v[188:191], v[118:121]
	v_mfma_f32_16x16x32_bf16 v[114:117], v[172:175], v[188:191], v[114:117]
	v_mfma_f32_16x16x32_bf16 v[86:89], v[164:167], v[206:209], v[86:89]
	v_mfma_f32_16x16x32_bf16 v[82:85], v[172:175], v[206:209], v[82:85]
	v_mfma_f32_16x16x32_bf16 v[70:73], v[164:167], v[214:217], v[70:73]
	v_mfma_f32_16x16x32_bf16 v[66:69], v[172:175], v[214:217], v[66:69]
	v_mfma_f32_16x16x32_bf16 v[134:137], v[168:171], v[184:187], v[134:137]
	v_mfma_f32_16x16x32_bf16 v[130:133], v[176:179], v[184:187], v[130:133]
	v_mfma_f32_16x16x32_bf16 v[118:121], v[168:171], v[192:195], v[118:121]
	v_mfma_f32_16x16x32_bf16 v[114:117], v[176:179], v[192:195], v[114:117]
	v_mfma_f32_16x16x32_bf16 v[86:89], v[168:171], v[210:213], v[86:89]
	v_mfma_f32_16x16x32_bf16 v[82:85], v[176:179], v[210:213], v[82:85]
	v_mfma_f32_16x16x32_bf16 v[70:73], v[168:171], v[218:221], v[70:73]
	v_mfma_f32_16x16x32_bf16 v[66:69], v[176:179], v[218:221], v[66:69]
	s_setprio 0
	s_barrier
	s_add_i32 s76, s76, s25
	v_lshl_add_u64 v[158:159], s[62:63], 0, v[0:1]
	s_mov_b32 m0, s76
	ds_read_b128 v[180:183], v162 offset:16384
	ds_read_b128 v[184:187], v162 offset:17408
	ds_read_b128 v[188:191], v162 offset:18432
	ds_read_b128 v[192:195], v162 offset:19456
	ds_read_b128 v[206:209], v162 offset:20480
	ds_read_b128 v[210:213], v162 offset:21504
	ds_read_b128 v[214:217], v162 offset:22528
	ds_read_b128 v[218:221], v162 offset:23552
	global_load_lds_dwordx4 v[158:159], off
	s_add_i32 m0, s76, 0x2000
	s_add_u32 s76, s62, 0x40000
	v_lshl_add_u64 v[222:223], s[62:63], 0, v[146:147]
	s_addc_u32 s77, s63, 0
	s_add_i32 s78, s78, s25
	global_load_lds_dwordx4 v[222:223], off
	v_lshl_add_u64 v[232:233], s[76:77], 0, v[0:1]
	s_mov_b32 m0, s78
	v_lshl_add_u64 v[234:235], s[64:65], 0, v[148:149]
	global_load_lds_dwordx4 v[232:233], off
	v_lshl_add_u64 v[232:233], s[76:77], 0, v[146:147]
	s_add_i32 m0, s78, 0x2000
	s_nop 0
	global_load_lds_dwordx4 v[232:233], off
	v_lshl_add_u64 v[232:233], s[64:65], 0, v[150:151]
	s_mov_b32 m0, s55
	s_nop 0
	global_load_lds_dwordx4 v[232:233], off
	s_mov_b32 m0, s56
	s_nop 0
	global_load_lds_dwordx4 v[234:235], off
	s_waitcnt vmcnt(8)
	s_waitcnt lgkmcnt(0)
	s_barrier
	s_setprio 1
	s_waitcnt lgkmcnt(0)
	v_mfma_f32_16x16x32_bf16 v[62:65], v[90:93], v[180:183], v[62:65]
	v_mfma_f32_16x16x32_bf16 v[58:61], v[98:101], v[180:183], v[58:61]
	v_mfma_f32_16x16x32_bf16 v[46:49], v[90:93], v[188:191], v[46:49]
	v_mfma_f32_16x16x32_bf16 v[42:45], v[98:101], v[188:191], v[42:45]
	v_mfma_f32_16x16x32_bf16 v[30:33], v[90:93], v[206:209], v[30:33]
	v_mfma_f32_16x16x32_bf16 v[26:29], v[98:101], v[206:209], v[26:29]
	v_mfma_f32_16x16x32_bf16 v[14:17], v[90:93], v[214:217], v[14:17]
	v_mfma_f32_16x16x32_bf16 v[10:13], v[98:101], v[214:217], v[10:13]
	v_mfma_f32_16x16x32_bf16 v[62:65], v[94:97], v[184:187], v[62:65]
	v_mfma_f32_16x16x32_bf16 v[58:61], v[102:105], v[184:187], v[58:61]
	v_mfma_f32_16x16x32_bf16 v[46:49], v[94:97], v[192:195], v[46:49]
	v_mfma_f32_16x16x32_bf16 v[42:45], v[102:105], v[192:195], v[42:45]
	v_mfma_f32_16x16x32_bf16 v[30:33], v[94:97], v[210:213], v[30:33]
	v_mfma_f32_16x16x32_bf16 v[26:29], v[102:105], v[210:213], v[26:29]
	v_mfma_f32_16x16x32_bf16 v[14:17], v[94:97], v[218:221], v[14:17]
	v_mfma_f32_16x16x32_bf16 v[10:13], v[102:105], v[218:221], v[10:13]
	v_mfma_f32_16x16x32_bf16 v[54:57], v[164:167], v[180:183], v[54:57]
	v_mfma_f32_16x16x32_bf16 v[50:53], v[172:175], v[180:183], v[50:53]
	v_mfma_f32_16x16x32_bf16 v[38:41], v[164:167], v[188:191], v[38:41]
	v_mfma_f32_16x16x32_bf16 v[34:37], v[172:175], v[188:191], v[34:37]
	v_mfma_f32_16x16x32_bf16 v[22:25], v[164:167], v[206:209], v[22:25]
	v_mfma_f32_16x16x32_bf16 v[18:21], v[172:175], v[206:209], v[18:21]
	v_mfma_f32_16x16x32_bf16 v[6:9], v[164:167], v[214:217], v[6:9]
	v_mfma_f32_16x16x32_bf16 v[2:5], v[172:175], v[214:217], v[2:5]
	v_mfma_f32_16x16x32_bf16 v[54:57], v[168:171], v[184:187], v[54:57]
	v_mfma_f32_16x16x32_bf16 v[50:53], v[176:179], v[184:187], v[50:53]
	v_mfma_f32_16x16x32_bf16 v[38:41], v[168:171], v[192:195], v[38:41]
	v_mfma_f32_16x16x32_bf16 v[34:37], v[176:179], v[192:195], v[34:37]
	v_mfma_f32_16x16x32_bf16 v[22:25], v[168:171], v[210:213], v[22:25]
	v_mfma_f32_16x16x32_bf16 v[18:21], v[176:179], v[210:213], v[18:21]
	v_mfma_f32_16x16x32_bf16 v[6:9], v[168:171], v[218:221], v[6:9]
	v_mfma_f32_16x16x32_bf16 v[2:5], v[176:179], v[218:221], v[2:5]
	s_setprio 0
	s_barrier
	s_add_i32 s76, 0, 0x18000
	s_add_i32 s77, 0, 0x1c000
	v_add_u32_e32 v102, s76, v160
	v_add_u32_e32 v163, s77, v160
	ds_read_b128 v[90:93], v102
	ds_read_b128 v[94:97], v102 offset:1024
	ds_read_b128 v[98:101], v102 offset:2048
	ds_read_b128 v[102:105], v102 offset:3072
	ds_read_b128 v[164:167], v163
	ds_read_b128 v[168:171], v163 offset:1024
	ds_read_b128 v[172:175], v163 offset:2048
	ds_read_b128 v[176:179], v163 offset:3072
	s_add_u32 s64, s64, 0x40000
	s_addc_u32 s65, s65, 0
	s_mov_b32 m0, s57
	v_lshl_add_u64 v[236:237], s[64:65], 0, v[150:151]
	ds_read_b128 v[180:183], v162 offset:32768
	ds_read_b128 v[184:187], v162 offset:33792
	ds_read_b128 v[188:191], v162 offset:34816
	ds_read_b128 v[192:195], v162 offset:35840
	ds_read_b128 v[206:209], v162 offset:36864
	ds_read_b128 v[210:213], v162 offset:37888
	ds_read_b128 v[214:217], v162 offset:38912
	ds_read_b128 v[218:221], v162 offset:39936
	global_load_lds_dwordx4 v[236:237], off
	v_lshl_add_u64 v[236:237], s[64:65], 0, v[148:149]
	s_mov_b32 m0, s66
	s_nop 0
	global_load_lds_dwordx4 v[236:237], off
	s_waitcnt vmcnt(8)
	s_waitcnt lgkmcnt(0)
	s_barrier
	s_setprio 1
	s_waitcnt lgkmcnt(0)
	v_mfma_f32_16x16x32_bf16 v[142:145], v[90:93], v[180:183], v[142:145]
	v_mfma_f32_16x16x32_bf16 v[138:141], v[98:101], v[180:183], v[138:141]
	v_mfma_f32_16x16x32_bf16 v[126:129], v[90:93], v[188:191], v[126:129]
	v_mfma_f32_16x16x32_bf16 v[122:125], v[98:101], v[188:191], v[122:125]
	v_mfma_f32_16x16x32_bf16 v[110:113], v[90:93], v[206:209], v[110:113]
	v_mfma_f32_16x16x32_bf16 v[106:109], v[98:101], v[206:209], v[106:109]
	v_mfma_f32_16x16x32_bf16 v[78:81], v[90:93], v[214:217], v[78:81]
	v_mfma_f32_16x16x32_bf16 v[74:77], v[98:101], v[214:217], v[74:77]
	v_mfma_f32_16x16x32_bf16 v[142:145], v[94:97], v[184:187], v[142:145]
	v_mfma_f32_16x16x32_bf16 v[138:141], v[102:105], v[184:187], v[138:141]
	v_mfma_f32_16x16x32_bf16 v[126:129], v[94:97], v[192:195], v[126:129]
	v_mfma_f32_16x16x32_bf16 v[122:125], v[102:105], v[192:195], v[122:125]
	v_mfma_f32_16x16x32_bf16 v[110:113], v[94:97], v[210:213], v[110:113]
	v_mfma_f32_16x16x32_bf16 v[106:109], v[102:105], v[210:213], v[106:109]
	v_mfma_f32_16x16x32_bf16 v[78:81], v[94:97], v[218:221], v[78:81]
	v_mfma_f32_16x16x32_bf16 v[74:77], v[102:105], v[218:221], v[74:77]
	v_mfma_f32_16x16x32_bf16 v[134:137], v[164:167], v[180:183], v[134:137]
	v_mfma_f32_16x16x32_bf16 v[130:133], v[172:175], v[180:183], v[130:133]
	v_mfma_f32_16x16x32_bf16 v[118:121], v[164:167], v[188:191], v[118:121]
	v_mfma_f32_16x16x32_bf16 v[114:117], v[172:175], v[188:191], v[114:117]
	v_mfma_f32_16x16x32_bf16 v[86:89], v[164:167], v[206:209], v[86:89]
	v_mfma_f32_16x16x32_bf16 v[82:85], v[172:175], v[206:209], v[82:85]
	v_mfma_f32_16x16x32_bf16 v[70:73], v[164:167], v[214:217], v[70:73]
	v_mfma_f32_16x16x32_bf16 v[66:69], v[172:175], v[214:217], v[66:69]
	v_mfma_f32_16x16x32_bf16 v[134:137], v[168:171], v[184:187], v[134:137]
	v_mfma_f32_16x16x32_bf16 v[130:133], v[176:179], v[184:187], v[130:133]
	v_mfma_f32_16x16x32_bf16 v[118:121], v[168:171], v[192:195], v[118:121]
	v_mfma_f32_16x16x32_bf16 v[114:117], v[176:179], v[192:195], v[114:117]
	v_mfma_f32_16x16x32_bf16 v[86:89], v[168:171], v[210:213], v[86:89]
	v_mfma_f32_16x16x32_bf16 v[82:85], v[176:179], v[210:213], v[82:85]
	v_mfma_f32_16x16x32_bf16 v[70:73], v[168:171], v[218:221], v[70:73]
	v_mfma_f32_16x16x32_bf16 v[66:69], v[176:179], v[218:221], v[66:69]
	s_setprio 0
	s_barrier
	s_add_i32 s64, s76, s25
	v_lshl_add_u64 v[158:159], v[158:159], 0, s[58:59]
	s_mov_b32 m0, s64
	ds_read_b128 v[180:183], v162 offset:49152
	ds_read_b128 v[184:187], v162 offset:50176
	ds_read_b128 v[188:191], v162 offset:51200
	ds_read_b128 v[192:195], v162 offset:52224
	ds_read_b128 v[206:209], v162 offset:53248
	ds_read_b128 v[210:213], v162 offset:54272
	ds_read_b128 v[214:217], v162 offset:55296
	ds_read_b128 v[218:221], v162 offset:56320
	global_load_lds_dwordx4 v[158:159], off
	s_add_i32 m0, s64, 0x2000
	s_add_u32 s62, s62, 0x40080
	v_lshl_add_u64 v[158:159], v[222:223], 0, s[58:59]
	s_addc_u32 s63, s63, 0
	s_add_i32 s64, s77, s25
	global_load_lds_dwordx4 v[158:159], off
	v_lshl_add_u64 v[158:159], s[62:63], 0, v[0:1]
	s_mov_b32 m0, s64
	s_nop 0
	global_load_lds_dwordx4 v[158:159], off
	v_lshl_add_u64 v[158:159], s[62:63], 0, v[146:147]
	s_add_i32 m0, s64, 0x2000
	s_nop 0
	global_load_lds_dwordx4 v[158:159], off
	v_lshl_add_u64 v[158:159], v[232:233], 0, s[58:59]
	s_mov_b32 m0, s30
	s_nop 0
	global_load_lds_dwordx4 v[158:159], off
	v_lshl_add_u64 v[158:159], v[234:235], 0, s[58:59]
	s_mov_b32 m0, s67
	s_nop 0
	global_load_lds_dwordx4 v[158:159], off
	s_waitcnt vmcnt(8)
	s_waitcnt lgkmcnt(0)
	s_barrier
	s_setprio 1
	s_waitcnt lgkmcnt(0)
	v_mfma_f32_16x16x32_bf16 v[62:65], v[90:93], v[180:183], v[62:65]
	v_mfma_f32_16x16x32_bf16 v[58:61], v[98:101], v[180:183], v[58:61]
	v_mfma_f32_16x16x32_bf16 v[46:49], v[90:93], v[188:191], v[46:49]
	v_mfma_f32_16x16x32_bf16 v[42:45], v[98:101], v[188:191], v[42:45]
	v_mfma_f32_16x16x32_bf16 v[30:33], v[90:93], v[206:209], v[30:33]
	v_mfma_f32_16x16x32_bf16 v[26:29], v[98:101], v[206:209], v[26:29]
	v_mfma_f32_16x16x32_bf16 v[14:17], v[90:93], v[214:217], v[14:17]
	v_mfma_f32_16x16x32_bf16 v[10:13], v[98:101], v[214:217], v[10:13]
	v_mfma_f32_16x16x32_bf16 v[62:65], v[94:97], v[184:187], v[62:65]
	v_mfma_f32_16x16x32_bf16 v[58:61], v[102:105], v[184:187], v[58:61]
	v_mfma_f32_16x16x32_bf16 v[46:49], v[94:97], v[192:195], v[46:49]
	v_mfma_f32_16x16x32_bf16 v[42:45], v[102:105], v[192:195], v[42:45]
	v_mfma_f32_16x16x32_bf16 v[30:33], v[94:97], v[210:213], v[30:33]
	v_mfma_f32_16x16x32_bf16 v[26:29], v[102:105], v[210:213], v[26:29]
	v_mfma_f32_16x16x32_bf16 v[14:17], v[94:97], v[218:221], v[14:17]
	v_mfma_f32_16x16x32_bf16 v[10:13], v[102:105], v[218:221], v[10:13]
	v_mfma_f32_16x16x32_bf16 v[54:57], v[164:167], v[180:183], v[54:57]
	v_mfma_f32_16x16x32_bf16 v[50:53], v[172:175], v[180:183], v[50:53]
	v_mfma_f32_16x16x32_bf16 v[38:41], v[164:167], v[188:191], v[38:41]
	v_mfma_f32_16x16x32_bf16 v[34:37], v[172:175], v[188:191], v[34:37]
	v_mfma_f32_16x16x32_bf16 v[22:25], v[164:167], v[206:209], v[22:25]
	v_mfma_f32_16x16x32_bf16 v[18:21], v[172:175], v[206:209], v[18:21]
	v_mfma_f32_16x16x32_bf16 v[6:9], v[164:167], v[214:217], v[6:9]
	v_mfma_f32_16x16x32_bf16 v[2:5], v[172:175], v[214:217], v[2:5]
	v_mfma_f32_16x16x32_bf16 v[54:57], v[168:171], v[184:187], v[54:57]
	v_mfma_f32_16x16x32_bf16 v[50:53], v[176:179], v[184:187], v[50:53]
	v_mfma_f32_16x16x32_bf16 v[38:41], v[168:171], v[192:195], v[38:41]
	v_mfma_f32_16x16x32_bf16 v[34:37], v[176:179], v[192:195], v[34:37]
	v_mfma_f32_16x16x32_bf16 v[22:25], v[168:171], v[210:213], v[22:25]
	v_mfma_f32_16x16x32_bf16 v[18:21], v[176:179], v[210:213], v[18:21]
	v_mfma_f32_16x16x32_bf16 v[6:9], v[168:171], v[218:221], v[6:9]
	v_mfma_f32_16x16x32_bf16 v[2:5], v[176:179], v[218:221], v[2:5]
	s_setprio 0
	s_barrier
	s_add_i32 s75, s75, 2
	s_add_u32 s60, s60, 0x100
	s_addc_u32 s61, s61, 0
	s_add_u32 s73, s73, 0x100
	s_addc_u32 s74, s74, 0
	s_cmp_gt_u32 s75, 13
	s_cbranch_scc0 .LBB0_537
	s_and_b64 vcc, exec, s[40:41]
	s_cbranch_vccz .LBB0_540
	s_barrier

.LBB0_616:
	s_add_u32 s62, s60, 0x100
	s_addc_u32 s63, s61, 0
	s_add_i32 s78, 0, 0x10000
	s_cmp_eq_u32 s77, 4
	s_cselect_b32 s67, s43, s63
	s_cselect_b32 s66, s42, s62
	v_add_u32_e32 v0, s78, v161
	s_cselect_b32 s65, s51, s76
	s_cselect_b32 s64, s50, s47
	s_add_i32 s79, 0, 0x14000
	ds_read_b128 v[132:135], v0
	ds_read_b128 v[136:139], v0 offset:1024
	ds_read_b128 v[154:157], v0 offset:2048
	ds_read_b128 v[164:167], v0 offset:3072
	v_add_u32_e32 v0, s79, v161
	ds_read_b128 v[168:171], v0
	ds_read_b128 v[172:175], v0 offset:1024
	ds_read_b128 v[176:179], v0 offset:2048
	ds_read_b128 v[180:183], v0 offset:3072
	v_lshl_add_u64 v[2:3], s[60:61], 0, v[150:151]
	s_add_i32 m0, s30, 0xc000
	ds_read_b128 v[184:187], v163
	ds_read_b128 v[188:191], v163 offset:1024
	ds_read_b128 v[192:195], v163 offset:2048
	ds_read_b128 v[206:209], v163 offset:3072
	ds_read_b128 v[210:213], v163 offset:4096
	ds_read_b128 v[214:217], v163 offset:5120
	ds_read_b128 v[218:221], v163 offset:6144
	ds_read_b128 v[232:235], v163 offset:7168
	global_load_lds_dwordx4 v[2:3], off
	v_lshl_add_u64 v[2:3], s[60:61], 0, v[152:153]
	s_add_i32 m0, s30, 0xe000
	s_nop 0
	global_load_lds_dwordx4 v[2:3], off
	s_waitcnt vmcnt(8)
	s_waitcnt lgkmcnt(0)
	s_barrier
	s_setprio 1
	s_waitcnt lgkmcnt(0)
	v_mfma_f32_16x16x32_bf16 v[128:131], v[132:135], v[184:187], v[128:131]
	v_mfma_f32_16x16x32_bf16 v[124:127], v[154:157], v[184:187], v[124:127]
	v_mfma_f32_16x16x32_bf16 v[120:123], v[132:135], v[192:195], v[120:123]
	v_mfma_f32_16x16x32_bf16 v[116:119], v[154:157], v[192:195], v[116:119]
	v_mfma_f32_16x16x32_bf16 v[112:115], v[132:135], v[210:213], v[112:115]
	v_mfma_f32_16x16x32_bf16 v[108:111], v[154:157], v[210:213], v[108:111]
	v_mfma_f32_16x16x32_bf16 v[104:107], v[132:135], v[218:221], v[104:107]
	v_mfma_f32_16x16x32_bf16 v[100:103], v[154:157], v[218:221], v[100:103]
	v_mfma_f32_16x16x32_bf16 v[128:131], v[136:139], v[188:191], v[128:131]
	v_mfma_f32_16x16x32_bf16 v[124:127], v[164:167], v[188:191], v[124:127]
	v_mfma_f32_16x16x32_bf16 v[120:123], v[136:139], v[206:209], v[120:123]
	v_mfma_f32_16x16x32_bf16 v[116:119], v[164:167], v[206:209], v[116:119]
	v_mfma_f32_16x16x32_bf16 v[112:115], v[136:139], v[214:217], v[112:115]
	v_mfma_f32_16x16x32_bf16 v[108:111], v[164:167], v[214:217], v[108:111]
	v_mfma_f32_16x16x32_bf16 v[104:107], v[136:139], v[232:235], v[104:107]
	v_mfma_f32_16x16x32_bf16 v[100:103], v[164:167], v[232:235], v[100:103]
	v_mfma_f32_16x16x32_bf16 v[96:99], v[168:171], v[184:187], v[96:99]
	v_mfma_f32_16x16x32_bf16 v[92:95], v[176:179], v[184:187], v[92:95]
	v_mfma_f32_16x16x32_bf16 v[88:91], v[168:171], v[192:195], v[88:91]
	v_mfma_f32_16x16x32_bf16 v[84:87], v[176:179], v[192:195], v[84:87]
	v_mfma_f32_16x16x32_bf16 v[80:83], v[168:171], v[210:213], v[80:83]
	v_mfma_f32_16x16x32_bf16 v[76:79], v[176:179], v[210:213], v[76:79]
	v_mfma_f32_16x16x32_bf16 v[72:75], v[168:171], v[218:221], v[72:75]
	v_mfma_f32_16x16x32_bf16 v[68:71], v[176:179], v[218:221], v[68:71]
	v_mfma_f32_16x16x32_bf16 v[96:99], v[172:175], v[188:191], v[96:99]
	v_mfma_f32_16x16x32_bf16 v[92:95], v[180:183], v[188:191], v[92:95]
	v_mfma_f32_16x16x32_bf16 v[88:91], v[172:175], v[206:209], v[88:91]
	v_mfma_f32_16x16x32_bf16 v[84:87], v[180:183], v[206:209], v[84:87]
	v_mfma_f32_16x16x32_bf16 v[80:83], v[172:175], v[214:217], v[80:83]
	v_mfma_f32_16x16x32_bf16 v[76:79], v[180:183], v[214:217], v[76:79]
	v_mfma_f32_16x16x32_bf16 v[72:75], v[172:175], v[232:235], v[72:75]
	v_mfma_f32_16x16x32_bf16 v[68:71], v[180:183], v[232:235], v[68:71]
	s_setprio 0
	s_barrier
	s_add_i32 s60, s78, s25
	v_lshl_add_u64 v[158:159], s[64:65], 0, v[144:145]
	s_mov_b32 m0, s60
	ds_read_b128 v[184:187], v163 offset:16384
	ds_read_b128 v[188:191], v163 offset:17408
	ds_read_b128 v[192:195], v163 offset:18432
	ds_read_b128 v[206:209], v163 offset:19456
	ds_read_b128 v[210:213], v163 offset:20480
	ds_read_b128 v[214:217], v163 offset:21504
	ds_read_b128 v[218:221], v163 offset:22528
	ds_read_b128 v[232:235], v163 offset:23552
	global_load_lds_dwordx4 v[158:159], off
	s_add_i32 m0, s60, 0x2000
	s_add_u32 s60, s64, 0x60000
	v_lshl_add_u64 v[222:223], s[64:65], 0, v[140:141]
	s_addc_u32 s61, s65, 0
	s_add_i32 s78, s79, s25
	global_load_lds_dwordx4 v[222:223], off
	v_lshl_add_u64 v[2:3], s[60:61], 0, v[144:145]
	s_mov_b32 m0, s78
	v_lshl_add_u64 v[236:237], s[66:67], 0, v[146:147]
	global_load_lds_dwordx4 v[2:3], off
	v_lshl_add_u64 v[2:3], s[60:61], 0, v[140:141]
	s_add_i32 m0, s78, 0x2000
	v_lshl_add_u64 v[238:239], s[66:67], 0, v[142:143]
	global_load_lds_dwordx4 v[2:3], off
	s_mov_b32 m0, s30
	s_nop 0
	global_load_lds_dwordx4 v[236:237], off
	s_mov_b32 m0, s55
	s_nop 0
	global_load_lds_dwordx4 v[238:239], off
	s_waitcnt vmcnt(8)
	s_waitcnt lgkmcnt(0)
	s_barrier
	s_setprio 1
	s_waitcnt lgkmcnt(0)
	v_mfma_f32_16x16x32_bf16 v[64:67], v[132:135], v[184:187], v[64:67]
	v_mfma_f32_16x16x32_bf16 v[60:63], v[154:157], v[184:187], v[60:63]
	v_mfma_f32_16x16x32_bf16 v[56:59], v[132:135], v[192:195], v[56:59]
	v_mfma_f32_16x16x32_bf16 v[52:55], v[154:157], v[192:195], v[52:55]
	v_mfma_f32_16x16x32_bf16 v[48:51], v[132:135], v[210:213], v[48:51]
	v_mfma_f32_16x16x32_bf16 v[44:47], v[154:157], v[210:213], v[44:47]
	v_mfma_f32_16x16x32_bf16 v[40:43], v[132:135], v[218:221], v[40:43]
	v_mfma_f32_16x16x32_bf16 v[36:39], v[154:157], v[218:221], v[36:39]
	v_mfma_f32_16x16x32_bf16 v[64:67], v[136:139], v[188:191], v[64:67]
	v_mfma_f32_16x16x32_bf16 v[60:63], v[164:167], v[188:191], v[60:63]
	v_mfma_f32_16x16x32_bf16 v[56:59], v[136:139], v[206:209], v[56:59]
	v_mfma_f32_16x16x32_bf16 v[52:55], v[164:167], v[206:209], v[52:55]
	v_mfma_f32_16x16x32_bf16 v[48:51], v[136:139], v[214:217], v[48:51]
	v_mfma_f32_16x16x32_bf16 v[44:47], v[164:167], v[214:217], v[44:47]
	v_mfma_f32_16x16x32_bf16 v[40:43], v[136:139], v[232:235], v[40:43]
	v_mfma_f32_16x16x32_bf16 v[36:39], v[164:167], v[232:235], v[36:39]
	v_mfma_f32_16x16x32_bf16 v[32:35], v[168:171], v[184:187], v[32:35]
	v_mfma_f32_16x16x32_bf16 v[28:31], v[176:179], v[184:187], v[28:31]
	v_mfma_f32_16x16x32_bf16 v[24:27], v[168:171], v[192:195], v[24:27]
	v_mfma_f32_16x16x32_bf16 v[20:23], v[176:179], v[192:195], v[20:23]
	v_mfma_f32_16x16x32_bf16 v[16:19], v[168:171], v[210:213], v[16:19]
	v_mfma_f32_16x16x32_bf16 v[12:15], v[176:179], v[210:213], v[12:15]
	v_mfma_f32_16x16x32_bf16 v[8:11], v[168:171], v[218:221], v[8:11]
	v_mfma_f32_16x16x32_bf16 v[2:5], v[176:179], v[218:221], v[4:7]
	v_mfma_f32_16x16x32_bf16 v[32:35], v[172:175], v[188:191], v[32:35]
	v_mfma_f32_16x16x32_bf16 v[28:31], v[180:183], v[188:191], v[28:31]
	v_mfma_f32_16x16x32_bf16 v[24:27], v[172:175], v[206:209], v[24:27]
	v_mfma_f32_16x16x32_bf16 v[20:23], v[180:183], v[206:209], v[20:23]
	v_mfma_f32_16x16x32_bf16 v[16:19], v[172:175], v[214:217], v[16:19]
	v_mfma_f32_16x16x32_bf16 v[12:15], v[180:183], v[214:217], v[12:15]
	v_mfma_f32_16x16x32_bf16 v[8:11], v[172:175], v[232:235], v[8:11]
	v_mfma_f32_16x16x32_bf16 v[2:5], v[180:183], v[232:235], v[2:5]
	s_setprio 0
	s_barrier
	s_add_i32 s78, 0, 0x18000
	v_add_u32_e32 v0, s78, v161
	s_add_i32 s79, 0, 0x1c000
	ds_read_b128 v[132:135], v0
	ds_read_b128 v[136:139], v0 offset:1024
	ds_read_b128 v[154:157], v0 offset:2048
	ds_read_b128 v[164:167], v0 offset:3072
	v_add_u32_e32 v0, s79, v161
	ds_read_b128 v[168:171], v0
	ds_read_b128 v[172:175], v0 offset:1024
	ds_read_b128 v[176:179], v0 offset:2048
	ds_read_b128 v[180:183], v0 offset:3072
	s_add_u32 s60, s66, 0x60000
	s_addc_u32 s61, s67, 0
	s_mov_b32 m0, s56
	v_lshl_add_u64 v[6:7], s[60:61], 0, v[146:147]
	ds_read_b128 v[184:187], v163 offset:32768
	ds_read_b128 v[188:191], v163 offset:33792
	ds_read_b128 v[192:195], v163 offset:34816
	ds_read_b128 v[206:209], v163 offset:35840
	ds_read_b128 v[210:213], v163 offset:36864
	ds_read_b128 v[214:217], v163 offset:37888
	ds_read_b128 v[218:221], v163 offset:38912
	ds_read_b128 v[232:235], v163 offset:39936
	global_load_lds_dwordx4 v[6:7], off
	v_lshl_add_u64 v[6:7], s[60:61], 0, v[142:143]
	s_mov_b32 m0, s57
	s_nop 0
	global_load_lds_dwordx4 v[6:7], off
	s_waitcnt vmcnt(8)
	s_waitcnt lgkmcnt(0)
	s_barrier
	s_setprio 1
	s_waitcnt lgkmcnt(0)
	v_mfma_f32_16x16x32_bf16 v[128:131], v[132:135], v[184:187], v[128:131]
	v_mfma_f32_16x16x32_bf16 v[124:127], v[154:157], v[184:187], v[124:127]
	v_mfma_f32_16x16x32_bf16 v[120:123], v[132:135], v[192:195], v[120:123]
	v_mfma_f32_16x16x32_bf16 v[116:119], v[154:157], v[192:195], v[116:119]
	v_mfma_f32_16x16x32_bf16 v[112:115], v[132:135], v[210:213], v[112:115]
	v_mfma_f32_16x16x32_bf16 v[108:111], v[154:157], v[210:213], v[108:111]
	v_mfma_f32_16x16x32_bf16 v[104:107], v[132:135], v[218:221], v[104:107]
	v_mfma_f32_16x16x32_bf16 v[100:103], v[154:157], v[218:221], v[100:103]
	v_mfma_f32_16x16x32_bf16 v[128:131], v[136:139], v[188:191], v[128:131]
	v_mfma_f32_16x16x32_bf16 v[124:127], v[164:167], v[188:191], v[124:127]
	v_mfma_f32_16x16x32_bf16 v[120:123], v[136:139], v[206:209], v[120:123]
	v_mfma_f32_16x16x32_bf16 v[116:119], v[164:167], v[206:209], v[116:119]
	v_mfma_f32_16x16x32_bf16 v[112:115], v[136:139], v[214:217], v[112:115]
	v_mfma_f32_16x16x32_bf16 v[108:111], v[164:167], v[214:217], v[108:111]
	v_mfma_f32_16x16x32_bf16 v[104:107], v[136:139], v[232:235], v[104:107]
	v_mfma_f32_16x16x32_bf16 v[100:103], v[164:167], v[232:235], v[100:103]
	v_mfma_f32_16x16x32_bf16 v[96:99], v[168:171], v[184:187], v[96:99]
	v_mfma_f32_16x16x32_bf16 v[92:95], v[176:179], v[184:187], v[92:95]
	v_mfma_f32_16x16x32_bf16 v[88:91], v[168:171], v[192:195], v[88:91]
	v_mfma_f32_16x16x32_bf16 v[84:87], v[176:179], v[192:195], v[84:87]
	v_mfma_f32_16x16x32_bf16 v[80:83], v[168:171], v[210:213], v[80:83]
	v_mfma_f32_16x16x32_bf16 v[76:79], v[176:179], v[210:213], v[76:79]
	v_mfma_f32_16x16x32_bf16 v[72:75], v[168:171], v[218:221], v[72:75]
	v_mfma_f32_16x16x32_bf16 v[68:71], v[176:179], v[218:221], v[68:71]
	v_mfma_f32_16x16x32_bf16 v[96:99], v[172:175], v[188:191], v[96:99]
	v_mfma_f32_16x16x32_bf16 v[92:95], v[180:183], v[188:191], v[92:95]
	v_mfma_f32_16x16x32_bf16 v[88:91], v[172:175], v[206:209], v[88:91]
	v_mfma_f32_16x16x32_bf16 v[84:87], v[180:183], v[206:209], v[84:87]
	v_mfma_f32_16x16x32_bf16 v[80:83], v[172:175], v[214:217], v[80:83]
	v_mfma_f32_16x16x32_bf16 v[76:79], v[180:183], v[214:217], v[76:79]
	v_mfma_f32_16x16x32_bf16 v[72:75], v[172:175], v[232:235], v[72:75]
	v_mfma_f32_16x16x32_bf16 v[68:71], v[180:183], v[232:235], v[68:71]
	s_setprio 0
	s_barrier
	s_add_i32 s60, s78, s25
	v_lshl_add_u64 v[6:7], v[158:159], 0, s[58:59]
	s_mov_b32 m0, s60
	ds_read_b128 v[184:187], v163 offset:49152
	ds_read_b128 v[188:191], v163 offset:50176
	ds_read_b128 v[192:195], v163 offset:51200
	ds_read_b128 v[206:209], v163 offset:52224
	ds_read_b128 v[210:213], v163 offset:53248
	ds_read_b128 v[214:217], v163 offset:54272
	ds_read_b128 v[218:221], v163 offset:55296
	ds_read_b128 v[232:235], v163 offset:56320
	global_load_lds_dwordx4 v[6:7], off
	s_add_i32 m0, s60, 0x2000
	s_add_u32 s60, s64, 0x60080
	v_lshl_add_u64 v[6:7], v[222:223], 0, s[58:59]
	s_addc_u32 s61, s65, 0
	s_add_i32 s64, s79, s25
	global_load_lds_dwordx4 v[6:7], off
	v_lshl_add_u64 v[6:7], s[60:61], 0, v[144:145]
	s_mov_b32 m0, s64
	s_nop 0
	global_load_lds_dwordx4 v[6:7], off
	v_lshl_add_u64 v[6:7], s[60:61], 0, v[140:141]
	s_add_i32 m0, s64, 0x2000
	s_nop 0
	global_load_lds_dwordx4 v[6:7], off
	v_lshl_add_u64 v[6:7], v[236:237], 0, s[58:59]
	s_mov_b32 m0, s68
	s_nop 0
	global_load_lds_dwordx4 v[6:7], off
	v_lshl_add_u64 v[6:7], v[238:239], 0, s[58:59]
	s_mov_b32 m0, s69
	s_nop 0
	global_load_lds_dwordx4 v[6:7], off
	s_waitcnt vmcnt(8)
	s_waitcnt lgkmcnt(0)
	s_barrier
	s_setprio 1
	s_waitcnt lgkmcnt(0)
	v_mfma_f32_16x16x32_bf16 v[64:67], v[132:135], v[184:187], v[64:67]
	v_mfma_f32_16x16x32_bf16 v[60:63], v[154:157], v[184:187], v[60:63]
	v_mfma_f32_16x16x32_bf16 v[56:59], v[132:135], v[192:195], v[56:59]
	v_mfma_f32_16x16x32_bf16 v[52:55], v[154:157], v[192:195], v[52:55]
	v_mfma_f32_16x16x32_bf16 v[48:51], v[132:135], v[210:213], v[48:51]
	v_mfma_f32_16x16x32_bf16 v[44:47], v[154:157], v[210:213], v[44:47]
	v_mfma_f32_16x16x32_bf16 v[40:43], v[132:135], v[218:221], v[40:43]
	v_mfma_f32_16x16x32_bf16 v[36:39], v[154:157], v[218:221], v[36:39]
	v_mfma_f32_16x16x32_bf16 v[64:67], v[136:139], v[188:191], v[64:67]
	v_mfma_f32_16x16x32_bf16 v[60:63], v[164:167], v[188:191], v[60:63]
	v_mfma_f32_16x16x32_bf16 v[56:59], v[136:139], v[206:209], v[56:59]
	v_mfma_f32_16x16x32_bf16 v[52:55], v[164:167], v[206:209], v[52:55]
	v_mfma_f32_16x16x32_bf16 v[48:51], v[136:139], v[214:217], v[48:51]
	v_mfma_f32_16x16x32_bf16 v[44:47], v[164:167], v[214:217], v[44:47]
	v_mfma_f32_16x16x32_bf16 v[40:43], v[136:139], v[232:235], v[40:43]
	v_mfma_f32_16x16x32_bf16 v[36:39], v[164:167], v[232:235], v[36:39]
	v_mfma_f32_16x16x32_bf16 v[32:35], v[168:171], v[184:187], v[32:35]
	v_mfma_f32_16x16x32_bf16 v[28:31], v[176:179], v[184:187], v[28:31]
	v_mfma_f32_16x16x32_bf16 v[24:27], v[168:171], v[192:195], v[24:27]
	v_mfma_f32_16x16x32_bf16 v[20:23], v[176:179], v[192:195], v[20:23]
	v_mfma_f32_16x16x32_bf16 v[16:19], v[168:171], v[210:213], v[16:19]
	v_mfma_f32_16x16x32_bf16 v[12:15], v[176:179], v[210:213], v[12:15]
	v_mfma_f32_16x16x32_bf16 v[6:9], v[168:171], v[218:221], v[8:11]
	v_mfma_f32_16x16x32_bf16 v[2:5], v[176:179], v[218:221], v[2:5]
	v_mfma_f32_16x16x32_bf16 v[32:35], v[172:175], v[188:191], v[32:35]
	v_mfma_f32_16x16x32_bf16 v[28:31], v[180:183], v[188:191], v[28:31]
	v_mfma_f32_16x16x32_bf16 v[24:27], v[172:175], v[206:209], v[24:27]
	v_mfma_f32_16x16x32_bf16 v[20:23], v[180:183], v[206:209], v[20:23]
	v_mfma_f32_16x16x32_bf16 v[16:19], v[172:175], v[214:217], v[16:19]
	v_mfma_f32_16x16x32_bf16 v[12:15], v[180:183], v[214:217], v[12:15]
	v_mfma_f32_16x16x32_bf16 v[8:11], v[172:175], v[232:235], v[6:9]
	v_mfma_f32_16x16x32_bf16 v[4:7], v[180:183], v[232:235], v[2:5]
	s_setprio 0
	s_barrier
	s_add_i32 s77, s77, 2
	s_add_u32 s47, s47, 0x100
	s_addc_u32 s76, s76, 0
	s_cmp_gt_u32 s77, 5
	s_mov_b64 s[60:61], s[62:63]
	s_cbranch_scc0 .LBB0_616
	s_and_b64 vcc, exec, s[44:45]
	s_cbranch_vccz .LBB0_619
	s_barrier

.LBB0_697:
	s_add_u32 s66, s64, 0xfffc0080
	s_addc_u32 s67, s65, -1
	s_add_i32 s81, 0, 0x10000
	s_cmp_eq_u32 s80, 12
	s_cselect_b32 s69, s51, s67
	s_cselect_b32 s68, s76, s66
	s_cselect_b32 s67, s47, s79
	s_cselect_b32 s66, s77, s78
	s_add_i32 s84, 0, 0x14000
	v_add_u32_e32 v156, s81, v145
	v_add_u32_e32 v172, s84, v145
	ds_read_b128 v[140:143], v156
	ds_read_b128 v[148:151], v156 offset:1024
	ds_read_b128 v[152:155], v156 offset:2048
	ds_read_b128 v[156:159], v156 offset:3072
	ds_read_b128 v[160:163], v172
	ds_read_b128 v[164:167], v172 offset:1024
	ds_read_b128 v[168:171], v172 offset:2048
	ds_read_b128 v[172:175], v172 offset:3072
	v_lshl_add_u64 v[218:219], s[64:65], 0, v[136:137]
	s_add_i32 m0, s55, 0xc000
	ds_read_b128 v[176:179], v147
	ds_read_b128 v[180:183], v147 offset:1024
	ds_read_b128 v[184:187], v147 offset:2048
	ds_read_b128 v[188:191], v147 offset:3072
	ds_read_b128 v[192:195], v147 offset:4096
	ds_read_b128 v[206:209], v147 offset:5120
	ds_read_b128 v[210:213], v147 offset:6144
	ds_read_b128 v[214:217], v147 offset:7168
	global_load_lds_dwordx4 v[218:219], off
	v_lshl_add_u64 v[218:219], s[64:65], 0, v[138:139]
	s_add_i32 m0, s55, 0xe000
	s_nop 0
	global_load_lds_dwordx4 v[218:219], off
	s_waitcnt vmcnt(8)
	s_waitcnt lgkmcnt(0)
	s_barrier
	s_setprio 1
	s_waitcnt lgkmcnt(0)
	v_mfma_f32_16x16x32_bf16 v[126:129], v[140:143], v[176:179], v[126:129]
	v_mfma_f32_16x16x32_bf16 v[122:125], v[152:155], v[176:179], v[122:125]
	v_mfma_f32_16x16x32_bf16 v[110:113], v[140:143], v[184:187], v[110:113]
	v_mfma_f32_16x16x32_bf16 v[106:109], v[152:155], v[184:187], v[106:109]
	v_mfma_f32_16x16x32_bf16 v[94:97], v[140:143], v[192:195], v[94:97]
	v_mfma_f32_16x16x32_bf16 v[90:93], v[152:155], v[192:195], v[90:93]
	v_mfma_f32_16x16x32_bf16 v[78:81], v[140:143], v[210:213], v[78:81]
	v_mfma_f32_16x16x32_bf16 v[74:77], v[152:155], v[210:213], v[74:77]
	v_mfma_f32_16x16x32_bf16 v[126:129], v[148:151], v[180:183], v[126:129]
	v_mfma_f32_16x16x32_bf16 v[122:125], v[156:159], v[180:183], v[122:125]
	v_mfma_f32_16x16x32_bf16 v[110:113], v[148:151], v[188:191], v[110:113]
	v_mfma_f32_16x16x32_bf16 v[106:109], v[156:159], v[188:191], v[106:109]
	v_mfma_f32_16x16x32_bf16 v[94:97], v[148:151], v[206:209], v[94:97]
	v_mfma_f32_16x16x32_bf16 v[90:93], v[156:159], v[206:209], v[90:93]
	v_mfma_f32_16x16x32_bf16 v[78:81], v[148:151], v[214:217], v[78:81]
	v_mfma_f32_16x16x32_bf16 v[74:77], v[156:159], v[214:217], v[74:77]
	v_mfma_f32_16x16x32_bf16 v[118:121], v[160:163], v[176:179], v[118:121]
	v_mfma_f32_16x16x32_bf16 v[114:117], v[168:171], v[176:179], v[114:117]
	v_mfma_f32_16x16x32_bf16 v[102:105], v[160:163], v[184:187], v[102:105]
	v_mfma_f32_16x16x32_bf16 v[98:101], v[168:171], v[184:187], v[98:101]
	v_mfma_f32_16x16x32_bf16 v[86:89], v[160:163], v[192:195], v[86:89]
	v_mfma_f32_16x16x32_bf16 v[82:85], v[168:171], v[192:195], v[82:85]
	v_mfma_f32_16x16x32_bf16 v[70:73], v[160:163], v[210:213], v[70:73]
	v_mfma_f32_16x16x32_bf16 v[66:69], v[168:171], v[210:213], v[66:69]
	v_mfma_f32_16x16x32_bf16 v[118:121], v[164:167], v[180:183], v[118:121]
	v_mfma_f32_16x16x32_bf16 v[114:117], v[172:175], v[180:183], v[114:117]
	v_mfma_f32_16x16x32_bf16 v[102:105], v[164:167], v[188:191], v[102:105]
	v_mfma_f32_16x16x32_bf16 v[98:101], v[172:175], v[188:191], v[98:101]
	v_mfma_f32_16x16x32_bf16 v[86:89], v[164:167], v[206:209], v[86:89]
	v_mfma_f32_16x16x32_bf16 v[82:85], v[172:175], v[206:209], v[82:85]
	v_mfma_f32_16x16x32_bf16 v[70:73], v[164:167], v[214:217], v[70:73]
	v_mfma_f32_16x16x32_bf16 v[66:69], v[172:175], v[214:217], v[66:69]
	s_setprio 0
	s_barrier
	s_add_i32 s81, s81, s25
	v_lshl_add_u64 v[218:219], s[66:67], 0, v[0:1]
	s_mov_b32 m0, s81
	ds_read_b128 v[176:179], v147 offset:16384
	ds_read_b128 v[180:183], v147 offset:17408
	ds_read_b128 v[184:187], v147 offset:18432
	ds_read_b128 v[188:191], v147 offset:19456
	ds_read_b128 v[192:195], v147 offset:20480
	ds_read_b128 v[206:209], v147 offset:21504
	ds_read_b128 v[210:213], v147 offset:22528
	ds_read_b128 v[214:217], v147 offset:23552
	global_load_lds_dwordx4 v[218:219], off
	s_add_i32 m0, s81, 0x2000
	s_add_u32 s82, s66, 0x40000
	v_lshl_add_u64 v[220:221], s[66:67], 0, v[130:131]
	s_addc_u32 s83, s67, 0
	s_add_i32 s81, s84, s25
	global_load_lds_dwordx4 v[220:221], off
	v_lshl_add_u64 v[222:223], s[82:83], 0, v[0:1]
	s_mov_b32 m0, s81
	v_lshl_add_u64 v[232:233], s[68:69], 0, v[132:133]
	global_load_lds_dwordx4 v[222:223], off
	v_lshl_add_u64 v[222:223], s[82:83], 0, v[130:131]
	s_add_i32 m0, s81, 0x2000
	s_nop 0
	global_load_lds_dwordx4 v[222:223], off
	v_lshl_add_u64 v[222:223], s[68:69], 0, v[134:135]
	s_mov_b32 m0, s55
	s_nop 0
	global_load_lds_dwordx4 v[222:223], off
	s_mov_b32 m0, s56
	s_nop 0
	global_load_lds_dwordx4 v[232:233], off
	s_waitcnt vmcnt(8)
	s_waitcnt lgkmcnt(0)
	s_barrier
	s_setprio 1
	s_waitcnt lgkmcnt(0)
	v_mfma_f32_16x16x32_bf16 v[62:65], v[140:143], v[176:179], v[62:65]
	v_mfma_f32_16x16x32_bf16 v[58:61], v[152:155], v[176:179], v[58:61]
	v_mfma_f32_16x16x32_bf16 v[46:49], v[140:143], v[184:187], v[46:49]
	v_mfma_f32_16x16x32_bf16 v[42:45], v[152:155], v[184:187], v[42:45]
	v_mfma_f32_16x16x32_bf16 v[30:33], v[140:143], v[192:195], v[30:33]
	v_mfma_f32_16x16x32_bf16 v[26:29], v[152:155], v[192:195], v[26:29]
	v_mfma_f32_16x16x32_bf16 v[14:17], v[140:143], v[210:213], v[14:17]
	v_mfma_f32_16x16x32_bf16 v[10:13], v[152:155], v[210:213], v[10:13]
	v_mfma_f32_16x16x32_bf16 v[62:65], v[148:151], v[180:183], v[62:65]
	v_mfma_f32_16x16x32_bf16 v[58:61], v[156:159], v[180:183], v[58:61]
	v_mfma_f32_16x16x32_bf16 v[46:49], v[148:151], v[188:191], v[46:49]
	v_mfma_f32_16x16x32_bf16 v[42:45], v[156:159], v[188:191], v[42:45]
	v_mfma_f32_16x16x32_bf16 v[30:33], v[148:151], v[206:209], v[30:33]
	v_mfma_f32_16x16x32_bf16 v[26:29], v[156:159], v[206:209], v[26:29]
	v_mfma_f32_16x16x32_bf16 v[14:17], v[148:151], v[214:217], v[14:17]
	v_mfma_f32_16x16x32_bf16 v[10:13], v[156:159], v[214:217], v[10:13]
	v_mfma_f32_16x16x32_bf16 v[54:57], v[160:163], v[176:179], v[54:57]
	v_mfma_f32_16x16x32_bf16 v[50:53], v[168:171], v[176:179], v[50:53]
	v_mfma_f32_16x16x32_bf16 v[38:41], v[160:163], v[184:187], v[38:41]
	v_mfma_f32_16x16x32_bf16 v[34:37], v[168:171], v[184:187], v[34:37]
	v_mfma_f32_16x16x32_bf16 v[22:25], v[160:163], v[192:195], v[22:25]
	v_mfma_f32_16x16x32_bf16 v[18:21], v[168:171], v[192:195], v[18:21]
	v_mfma_f32_16x16x32_bf16 v[6:9], v[160:163], v[210:213], v[6:9]
	v_mfma_f32_16x16x32_bf16 v[2:5], v[168:171], v[210:213], v[2:5]
	v_mfma_f32_16x16x32_bf16 v[54:57], v[164:167], v[180:183], v[54:57]
	v_mfma_f32_16x16x32_bf16 v[50:53], v[172:175], v[180:183], v[50:53]
	v_mfma_f32_16x16x32_bf16 v[38:41], v[164:167], v[188:191], v[38:41]
	v_mfma_f32_16x16x32_bf16 v[34:37], v[172:175], v[188:191], v[34:37]
	v_mfma_f32_16x16x32_bf16 v[22:25], v[164:167], v[206:209], v[22:25]
	v_mfma_f32_16x16x32_bf16 v[18:21], v[172:175], v[206:209], v[18:21]
	v_mfma_f32_16x16x32_bf16 v[6:9], v[164:167], v[214:217], v[6:9]
	v_mfma_f32_16x16x32_bf16 v[2:5], v[172:175], v[214:217], v[2:5]
	s_setprio 0
	s_barrier
	s_add_i32 s81, 0, 0x18000
	s_add_i32 s82, 0, 0x1c000
	v_add_u32_e32 v156, s81, v145
	v_add_u32_e32 v172, s82, v145
	ds_read_b128 v[140:143], v156
	ds_read_b128 v[148:151], v156 offset:1024
	ds_read_b128 v[152:155], v156 offset:2048
	ds_read_b128 v[156:159], v156 offset:3072
	ds_read_b128 v[160:163], v172
	ds_read_b128 v[164:167], v172 offset:1024
	ds_read_b128 v[168:171], v172 offset:2048
	ds_read_b128 v[172:175], v172 offset:3072
	s_add_u32 s68, s68, 0x40000
	s_addc_u32 s69, s69, 0
	s_mov_b32 m0, s57
	v_lshl_add_u64 v[234:235], s[68:69], 0, v[134:135]
	ds_read_b128 v[176:179], v147 offset:32768
	ds_read_b128 v[180:183], v147 offset:33792
	ds_read_b128 v[184:187], v147 offset:34816
	ds_read_b128 v[188:191], v147 offset:35840
	ds_read_b128 v[192:195], v147 offset:36864
	ds_read_b128 v[206:209], v147 offset:37888
	ds_read_b128 v[210:213], v147 offset:38912
	ds_read_b128 v[214:217], v147 offset:39936
	global_load_lds_dwordx4 v[234:235], off
	v_lshl_add_u64 v[234:235], s[68:69], 0, v[132:133]
	s_mov_b32 m0, s70
	s_nop 0
	global_load_lds_dwordx4 v[234:235], off
	s_waitcnt vmcnt(8)
	s_waitcnt lgkmcnt(0)
	s_barrier
	s_setprio 1
	s_waitcnt lgkmcnt(0)
	v_mfma_f32_16x16x32_bf16 v[126:129], v[140:143], v[176:179], v[126:129]
	v_mfma_f32_16x16x32_bf16 v[122:125], v[152:155], v[176:179], v[122:125]
	v_mfma_f32_16x16x32_bf16 v[110:113], v[140:143], v[184:187], v[110:113]
	v_mfma_f32_16x16x32_bf16 v[106:109], v[152:155], v[184:187], v[106:109]
	v_mfma_f32_16x16x32_bf16 v[94:97], v[140:143], v[192:195], v[94:97]
	v_mfma_f32_16x16x32_bf16 v[90:93], v[152:155], v[192:195], v[90:93]
	v_mfma_f32_16x16x32_bf16 v[78:81], v[140:143], v[210:213], v[78:81]
	v_mfma_f32_16x16x32_bf16 v[74:77], v[152:155], v[210:213], v[74:77]
	v_mfma_f32_16x16x32_bf16 v[126:129], v[148:151], v[180:183], v[126:129]
	v_mfma_f32_16x16x32_bf16 v[122:125], v[156:159], v[180:183], v[122:125]
	v_mfma_f32_16x16x32_bf16 v[110:113], v[148:151], v[188:191], v[110:113]
	v_mfma_f32_16x16x32_bf16 v[106:109], v[156:159], v[188:191], v[106:109]
	v_mfma_f32_16x16x32_bf16 v[94:97], v[148:151], v[206:209], v[94:97]
	v_mfma_f32_16x16x32_bf16 v[90:93], v[156:159], v[206:209], v[90:93]
	v_mfma_f32_16x16x32_bf16 v[78:81], v[148:151], v[214:217], v[78:81]
	v_mfma_f32_16x16x32_bf16 v[74:77], v[156:159], v[214:217], v[74:77]
	v_mfma_f32_16x16x32_bf16 v[118:121], v[160:163], v[176:179], v[118:121]
	v_mfma_f32_16x16x32_bf16 v[114:117], v[168:171], v[176:179], v[114:117]
	v_mfma_f32_16x16x32_bf16 v[102:105], v[160:163], v[184:187], v[102:105]
	v_mfma_f32_16x16x32_bf16 v[98:101], v[168:171], v[184:187], v[98:101]
	v_mfma_f32_16x16x32_bf16 v[86:89], v[160:163], v[192:195], v[86:89]
	v_mfma_f32_16x16x32_bf16 v[82:85], v[168:171], v[192:195], v[82:85]
	v_mfma_f32_16x16x32_bf16 v[70:73], v[160:163], v[210:213], v[70:73]
	v_mfma_f32_16x16x32_bf16 v[66:69], v[168:171], v[210:213], v[66:69]
	v_mfma_f32_16x16x32_bf16 v[118:121], v[164:167], v[180:183], v[118:121]
	v_mfma_f32_16x16x32_bf16 v[114:117], v[172:175], v[180:183], v[114:117]
	v_mfma_f32_16x16x32_bf16 v[102:105], v[164:167], v[188:191], v[102:105]
	v_mfma_f32_16x16x32_bf16 v[98:101], v[172:175], v[188:191], v[98:101]
	v_mfma_f32_16x16x32_bf16 v[86:89], v[164:167], v[206:209], v[86:89]
	v_mfma_f32_16x16x32_bf16 v[82:85], v[172:175], v[206:209], v[82:85]
	v_mfma_f32_16x16x32_bf16 v[70:73], v[164:167], v[214:217], v[70:73]
	v_mfma_f32_16x16x32_bf16 v[66:69], v[172:175], v[214:217], v[66:69]
	s_setprio 0
	s_barrier
	s_add_i32 s68, s81, s25
	v_lshl_add_u64 v[218:219], v[218:219], 0, s[58:59]
	s_mov_b32 m0, s68
	ds_read_b128 v[176:179], v147 offset:49152
	ds_read_b128 v[180:183], v147 offset:50176
	ds_read_b128 v[184:187], v147 offset:51200
	ds_read_b128 v[188:191], v147 offset:52224
	ds_read_b128 v[192:195], v147 offset:53248
	ds_read_b128 v[206:209], v147 offset:54272
	ds_read_b128 v[210:213], v147 offset:55296
	ds_read_b128 v[214:217], v147 offset:56320
	global_load_lds_dwordx4 v[218:219], off
	s_add_i32 m0, s68, 0x2000
	s_add_u32 s66, s66, 0x40080
	v_lshl_add_u64 v[218:219], v[220:221], 0, s[58:59]
	s_addc_u32 s67, s67, 0
	s_add_i32 s68, s82, s25
	global_load_lds_dwordx4 v[218:219], off
	v_lshl_add_u64 v[218:219], s[66:67], 0, v[0:1]
	s_mov_b32 m0, s68
	s_nop 0
	global_load_lds_dwordx4 v[218:219], off
	v_lshl_add_u64 v[218:219], s[66:67], 0, v[130:131]
	s_add_i32 m0, s68, 0x2000
	s_nop 0
	global_load_lds_dwordx4 v[218:219], off
	v_lshl_add_u64 v[218:219], v[222:223], 0, s[58:59]
	s_mov_b32 m0, s72
	s_nop 0
	global_load_lds_dwordx4 v[218:219], off
	v_lshl_add_u64 v[218:219], v[232:233], 0, s[58:59]
	s_mov_b32 m0, s73
	s_nop 0
	global_load_lds_dwordx4 v[218:219], off
	s_waitcnt vmcnt(8)
	s_waitcnt lgkmcnt(0)
	s_barrier
	s_setprio 1
	s_waitcnt lgkmcnt(0)
	v_mfma_f32_16x16x32_bf16 v[62:65], v[140:143], v[176:179], v[62:65]
	v_mfma_f32_16x16x32_bf16 v[58:61], v[152:155], v[176:179], v[58:61]
	v_mfma_f32_16x16x32_bf16 v[46:49], v[140:143], v[184:187], v[46:49]
	v_mfma_f32_16x16x32_bf16 v[42:45], v[152:155], v[184:187], v[42:45]
	v_mfma_f32_16x16x32_bf16 v[30:33], v[140:143], v[192:195], v[30:33]
	v_mfma_f32_16x16x32_bf16 v[26:29], v[152:155], v[192:195], v[26:29]
	v_mfma_f32_16x16x32_bf16 v[14:17], v[140:143], v[210:213], v[14:17]
	v_mfma_f32_16x16x32_bf16 v[10:13], v[152:155], v[210:213], v[10:13]
	v_mfma_f32_16x16x32_bf16 v[62:65], v[148:151], v[180:183], v[62:65]
	v_mfma_f32_16x16x32_bf16 v[58:61], v[156:159], v[180:183], v[58:61]
	v_mfma_f32_16x16x32_bf16 v[46:49], v[148:151], v[188:191], v[46:49]
	v_mfma_f32_16x16x32_bf16 v[42:45], v[156:159], v[188:191], v[42:45]
	v_mfma_f32_16x16x32_bf16 v[30:33], v[148:151], v[206:209], v[30:33]
	v_mfma_f32_16x16x32_bf16 v[26:29], v[156:159], v[206:209], v[26:29]
	v_mfma_f32_16x16x32_bf16 v[14:17], v[148:151], v[214:217], v[14:17]
	v_mfma_f32_16x16x32_bf16 v[10:13], v[156:159], v[214:217], v[10:13]
	v_mfma_f32_16x16x32_bf16 v[54:57], v[160:163], v[176:179], v[54:57]
	v_mfma_f32_16x16x32_bf16 v[50:53], v[168:171], v[176:179], v[50:53]
	v_mfma_f32_16x16x32_bf16 v[38:41], v[160:163], v[184:187], v[38:41]
	v_mfma_f32_16x16x32_bf16 v[34:37], v[168:171], v[184:187], v[34:37]
	v_mfma_f32_16x16x32_bf16 v[22:25], v[160:163], v[192:195], v[22:25]
	v_mfma_f32_16x16x32_bf16 v[18:21], v[168:171], v[192:195], v[18:21]
	v_mfma_f32_16x16x32_bf16 v[6:9], v[160:163], v[210:213], v[6:9]
	v_mfma_f32_16x16x32_bf16 v[2:5], v[168:171], v[210:213], v[2:5]
	v_mfma_f32_16x16x32_bf16 v[54:57], v[164:167], v[180:183], v[54:57]
	v_mfma_f32_16x16x32_bf16 v[50:53], v[172:175], v[180:183], v[50:53]
	v_mfma_f32_16x16x32_bf16 v[38:41], v[164:167], v[188:191], v[38:41]
	v_mfma_f32_16x16x32_bf16 v[34:37], v[172:175], v[188:191], v[34:37]
	v_mfma_f32_16x16x32_bf16 v[22:25], v[164:167], v[206:209], v[22:25]
	v_mfma_f32_16x16x32_bf16 v[18:21], v[172:175], v[206:209], v[18:21]
	v_mfma_f32_16x16x32_bf16 v[6:9], v[164:167], v[214:217], v[6:9]
	v_mfma_f32_16x16x32_bf16 v[2:5], v[172:175], v[214:217], v[2:5]
	s_setprio 0
	s_barrier
	s_add_i32 s80, s80, 2
	s_add_u32 s64, s64, 0x100
	s_addc_u32 s65, s65, 0
	s_add_u32 s78, s78, 0x100
	s_addc_u32 s79, s79, 0
	s_cmp_gt_u32 s80, 13
	s_cbranch_scc0 .LBB0_697
	s_and_b64 vcc, exec, s[44:45]
	s_cbranch_vccz .LBB0_700
	s_barrier
